# GU: first K-tile after an epilogue waits with vmcnt(16) so the 8 epilogue stores may stay outstanding (in-order queue), instead of draining them
# speedup vs baseline: 1.0058x; 1.0058x over previous
; DI unsigned pk2(float lo, float hi) { const f32x2 v = {lo, hi}; return __builtin_bit_cast(unsigned, __builtin_convertvector(v, bf2_t)); }
; DI void gemm_gu(const Params& p, size_t woff, int bid, int nb, char* smem, const int tid) {
;     ...
;         const int nb0 = n0 + wn * 64;
; #pragma unroll
;         for (int mi = 0; mi < 4; ++mi) {
;             const int row = m0 + wm * 64 + mi * 16 + r;
; #pragma unroll
;             for (int pr = 0; pr < 2; ++pr) {
;                 const f32x4 g = acc[mi][2 * pr], u = acc[mi][2 * pr + 1];
;                 float o[4];
; #pragma unroll
;                 for (int j = 0; j < 4; ++j) o[j] = g[j] * __builtin_amdgcn_rcpf(1.0f + __builtin_amdgcn_exp2f(-LOG2E * g[j])) * u[j];
;                 const int col = ((nb0 + pr * 32) >> 5) * 16 + q * 4;
;                 u32x2 w; w.x = pk2(o[0], o[1]); w.y = pk2(o[2], o[3]);
;                 *(u32x2*)(ACT + (size_t)row * DFF + col) = w;
;             }
;         }
.Lgu_epi:
	s_mul_i32 s1, s57, 0x160000
	s_lshl_b32 s62, s58, 8
	s_add_u32 s1, s1, s62
	s_add_u32 s1, s1, 0x52c0000
	s_add_u32 s2, s88, s1
	s_addc_u32 s3, s89, 0
	s_nop 7
	s_nop 7
	v_mul_f32_e32 v152, 0xbfb8aa3b, v24
	v_mul_f32_e32 v153, 0xbfb8aa3b, v25
	v_mul_f32_e32 v154, 0xbfb8aa3b, v26
	v_mul_f32_e32 v155, 0xbfb8aa3b, v27
	v_exp_f32_e32 v152, v152
	v_exp_f32_e32 v153, v153
	v_exp_f32_e32 v154, v154
	v_exp_f32_e32 v155, v155
	s_nop 0
	v_add_f32_e32 v152, 1.0, v152
	v_add_f32_e32 v153, 1.0, v153
	v_add_f32_e32 v154, 1.0, v154
	v_add_f32_e32 v155, 1.0, v155
	v_rcp_f32_e32 v152, v152
	v_rcp_f32_e32 v153, v153
	v_rcp_f32_e32 v154, v154
	v_rcp_f32_e32 v155, v155
	s_nop 0
	v_pk_mul_f32 v[152:153], v[24:25], v[152:153]
	v_pk_mul_f32 v[154:155], v[26:27], v[154:155]
	v_pk_mul_f32 v[152:153], v[28:29], v[152:153]
	v_pk_mul_f32 v[154:155], v[30:31], v[154:155]
	v_cvt_pk_bf16_f32 v152, v152, v153
	v_cvt_pk_bf16_f32 v153, v154, v155
	v_mul_f32_e32 v156, 0xbfb8aa3b, v32
	v_mul_f32_e32 v157, 0xbfb8aa3b, v33
	v_mul_f32_e32 v158, 0xbfb8aa3b, v34
	v_mul_f32_e32 v159, 0xbfb8aa3b, v35
	v_exp_f32_e32 v156, v156
	v_exp_f32_e32 v157, v157
	v_exp_f32_e32 v158, v158
	v_exp_f32_e32 v159, v159
	s_nop 0
	v_add_f32_e32 v156, 1.0, v156
	v_add_f32_e32 v157, 1.0, v157
	v_add_f32_e32 v158, 1.0, v158
	v_add_f32_e32 v159, 1.0, v159
	v_rcp_f32_e32 v156, v156
	v_rcp_f32_e32 v157, v157
	v_rcp_f32_e32 v158, v158
	v_rcp_f32_e32 v159, v159
	s_nop 0
	v_pk_mul_f32 v[156:157], v[32:33], v[156:157]
	v_pk_mul_f32 v[158:159], v[34:35], v[158:159]
	v_pk_mul_f32 v[156:157], v[36:37], v[156:157]
	v_pk_mul_f32 v[158:159], v[38:39], v[158:159]
	v_cvt_pk_bf16_f32 v154, v156, v157
	v_cvt_pk_bf16_f32 v155, v158, v159
	s_nop 1
	v_permlane16_swap_b32_e32 v152, v154
	v_permlane16_swap_b32_e32 v153, v155
	global_store_dwordx4 v237, v[152:155], s[2:3] offset:0
	v_mul_f32_e32 v160, 0xbfb8aa3b, v56
	v_mul_f32_e32 v161, 0xbfb8aa3b, v57
	v_mul_f32_e32 v162, 0xbfb8aa3b, v58
	v_mul_f32_e32 v163, 0xbfb8aa3b, v59
	v_exp_f32_e32 v160, v160
	v_exp_f32_e32 v161, v161
	v_exp_f32_e32 v162, v162
	v_exp_f32_e32 v163, v163
	s_nop 0
	v_add_f32_e32 v160, 1.0, v160
	v_add_f32_e32 v161, 1.0, v161
	v_add_f32_e32 v162, 1.0, v162
	v_add_f32_e32 v163, 1.0, v163
	v_rcp_f32_e32 v160, v160
	v_rcp_f32_e32 v161, v161
	v_rcp_f32_e32 v162, v162
	v_rcp_f32_e32 v163, v163
	s_nop 0
	v_pk_mul_f32 v[160:161], v[56:57], v[160:161]
	v_pk_mul_f32 v[162:163], v[58:59], v[162:163]
	v_pk_mul_f32 v[160:161], v[60:61], v[160:161]
	v_pk_mul_f32 v[162:163], v[62:63], v[162:163]
	v_cvt_pk_bf16_f32 v160, v160, v161
	v_cvt_pk_bf16_f32 v161, v162, v163
	v_mul_f32_e32 v164, 0xbfb8aa3b, v64
	v_mul_f32_e32 v165, 0xbfb8aa3b, v65
	v_mul_f32_e32 v166, 0xbfb8aa3b, v66
	v_mul_f32_e32 v167, 0xbfb8aa3b, v67
	v_exp_f32_e32 v164, v164
	v_exp_f32_e32 v165, v165
	v_exp_f32_e32 v166, v166
	v_exp_f32_e32 v167, v167
	s_nop 0
	v_add_f32_e32 v164, 1.0, v164
	v_add_f32_e32 v165, 1.0, v165
	v_add_f32_e32 v166, 1.0, v166
	v_add_f32_e32 v167, 1.0, v167
	v_rcp_f32_e32 v164, v164
	v_rcp_f32_e32 v165, v165
	v_rcp_f32_e32 v166, v166
	v_rcp_f32_e32 v167, v167
	s_nop 0
	v_pk_mul_f32 v[164:165], v[64:65], v[164:165]
	v_pk_mul_f32 v[166:167], v[66:67], v[166:167]
	v_pk_mul_f32 v[164:165], v[68:69], v[164:165]
	v_pk_mul_f32 v[166:167], v[70:71], v[166:167]
	v_cvt_pk_bf16_f32 v162, v164, v165
	v_cvt_pk_bf16_f32 v163, v166, v167
	s_nop 1
	v_permlane16_swap_b32_e32 v160, v162
	v_permlane16_swap_b32_e32 v161, v163
	global_store_dwordx4 v237, v[160:163], s[2:3] offset:128
	s_add_u32 s2, s2, 0x2c000
	s_addc_u32 s3, s3, 0
	v_mul_f32_e32 v168, 0xbfb8aa3b, v40
	v_mul_f32_e32 v169, 0xbfb8aa3b, v41
	v_mul_f32_e32 v170, 0xbfb8aa3b, v42
	v_mul_f32_e32 v171, 0xbfb8aa3b, v43
	v_exp_f32_e32 v168, v168
	v_exp_f32_e32 v169, v169
	v_exp_f32_e32 v170, v170
	v_exp_f32_e32 v171, v171
	s_nop 0
	v_add_f32_e32 v168, 1.0, v168
	v_add_f32_e32 v169, 1.0, v169
	v_add_f32_e32 v170, 1.0, v170
	v_add_f32_e32 v171, 1.0, v171
	v_rcp_f32_e32 v168, v168
	v_rcp_f32_e32 v169, v169
	v_rcp_f32_e32 v170, v170
	v_rcp_f32_e32 v171, v171
	s_nop 0
	v_pk_mul_f32 v[168:169], v[40:41], v[168:169]
	v_pk_mul_f32 v[170:171], v[42:43], v[170:171]
	v_pk_mul_f32 v[168:169], v[44:45], v[168:169]
	v_pk_mul_f32 v[170:171], v[46:47], v[170:171]
	v_cvt_pk_bf16_f32 v168, v168, v169
	v_cvt_pk_bf16_f32 v169, v170, v171
	v_mul_f32_e32 v172, 0xbfb8aa3b, v48
	v_mul_f32_e32 v173, 0xbfb8aa3b, v49
	v_mul_f32_e32 v174, 0xbfb8aa3b, v50
	v_mul_f32_e32 v175, 0xbfb8aa3b, v51
	v_exp_f32_e32 v172, v172
	v_exp_f32_e32 v173, v173
	v_exp_f32_e32 v174, v174
	v_exp_f32_e32 v175, v175
	s_nop 0
	v_add_f32_e32 v172, 1.0, v172
	v_add_f32_e32 v173, 1.0, v173
	v_add_f32_e32 v174, 1.0, v174
	v_add_f32_e32 v175, 1.0, v175
	v_rcp_f32_e32 v172, v172
	v_rcp_f32_e32 v173, v173
	v_rcp_f32_e32 v174, v174
	v_rcp_f32_e32 v175, v175
	s_nop 0
	v_pk_mul_f32 v[172:173], v[48:49], v[172:173]
	v_pk_mul_f32 v[174:175], v[50:51], v[174:175]
	v_pk_mul_f32 v[172:173], v[52:53], v[172:173]
	v_pk_mul_f32 v[174:175], v[54:55], v[174:175]
	v_cvt_pk_bf16_f32 v170, v172, v173
	v_cvt_pk_bf16_f32 v171, v174, v175
	s_nop 1
	v_permlane16_swap_b32_e32 v168, v170
	v_permlane16_swap_b32_e32 v169, v171
	global_store_dwordx4 v237, v[168:171], s[2:3] offset:0
	v_mul_f32_e32 v152, 0xbfb8aa3b, v72
	v_mul_f32_e32 v153, 0xbfb8aa3b, v73
	v_mul_f32_e32 v154, 0xbfb8aa3b, v74
	v_mul_f32_e32 v155, 0xbfb8aa3b, v75
	v_exp_f32_e32 v152, v152
	v_exp_f32_e32 v153, v153
	v_exp_f32_e32 v154, v154
	v_exp_f32_e32 v155, v155
	s_nop 0
	v_add_f32_e32 v152, 1.0, v152
	v_add_f32_e32 v153, 1.0, v153
	v_add_f32_e32 v154, 1.0, v154
	v_add_f32_e32 v155, 1.0, v155
	v_rcp_f32_e32 v152, v152
	v_rcp_f32_e32 v153, v153
; DI unsigned pk2(float lo, float hi) { const f32x2 v = {lo, hi}; return __builtin_bit_cast(unsigned, __builtin_convertvector(v, bf2_t)); }
; DI void gemm_gu(const Params& p, size_t woff, int bid, int nb, char* smem, const int tid) {
;     ...
;         const int nb0 = n0 + wn * 64;
; #pragma unroll
;         for (int mi = 0; mi < 4; ++mi) {
;             const int row = m0 + wm * 64 + mi * 16 + r;
; #pragma unroll
;             for (int pr = 0; pr < 2; ++pr) {
;                 const f32x4 g = acc[mi][2 * pr], u = acc[mi][2 * pr + 1];
;                 float o[4];
; #pragma unroll
;                 for (int j = 0; j < 4; ++j) o[j] = g[j] * __builtin_amdgcn_rcpf(1.0f + __builtin_amdgcn_exp2f(-LOG2E * g[j])) * u[j];
;                 const int col = ((nb0 + pr * 32) >> 5) * 16 + q * 4;
;                 u32x2 w; w.x = pk2(o[0], o[1]); w.y = pk2(o[2], o[3]);
;                 *(u32x2*)(ACT + (size_t)row * DFF + col) = w;
;             }
;         }
	v_rcp_f32_e32 v154, v154
	v_rcp_f32_e32 v155, v155
	s_nop 0
	v_pk_mul_f32 v[152:153], v[72:73], v[152:153]
	v_pk_mul_f32 v[154:155], v[74:75], v[154:155]
	v_pk_mul_f32 v[152:153], v[76:77], v[152:153]
	v_pk_mul_f32 v[154:155], v[78:79], v[154:155]
	v_cvt_pk_bf16_f32 v152, v152, v153
	v_cvt_pk_bf16_f32 v153, v154, v155
	v_mul_f32_e32 v156, 0xbfb8aa3b, v80
	v_mul_f32_e32 v157, 0xbfb8aa3b, v81
	v_mul_f32_e32 v158, 0xbfb8aa3b, v82
	v_mul_f32_e32 v159, 0xbfb8aa3b, v83
	v_exp_f32_e32 v156, v156
	v_exp_f32_e32 v157, v157
	v_exp_f32_e32 v158, v158
	v_exp_f32_e32 v159, v159
	s_nop 0
	v_add_f32_e32 v156, 1.0, v156
	v_add_f32_e32 v157, 1.0, v157
	v_add_f32_e32 v158, 1.0, v158
	v_add_f32_e32 v159, 1.0, v159
	v_rcp_f32_e32 v156, v156
	v_rcp_f32_e32 v157, v157
	v_rcp_f32_e32 v158, v158
	v_rcp_f32_e32 v159, v159
	s_nop 0
	v_pk_mul_f32 v[156:157], v[80:81], v[156:157]
	v_pk_mul_f32 v[158:159], v[82:83], v[158:159]
	v_pk_mul_f32 v[156:157], v[84:85], v[156:157]
	v_pk_mul_f32 v[158:159], v[86:87], v[158:159]
	v_cvt_pk_bf16_f32 v154, v156, v157
	v_cvt_pk_bf16_f32 v155, v158, v159
	s_nop 1
	v_permlane16_swap_b32_e32 v152, v154
	v_permlane16_swap_b32_e32 v153, v155
	global_store_dwordx4 v237, v[152:155], s[2:3] offset:128
	s_add_u32 s2, s2, 0x84000
	s_addc_u32 s3, s3, 0
	v_mul_f32_e32 v160, 0xbfb8aa3b, v88
	v_mul_f32_e32 v161, 0xbfb8aa3b, v89
	v_mul_f32_e32 v162, 0xbfb8aa3b, v90
	v_mul_f32_e32 v163, 0xbfb8aa3b, v91
	v_exp_f32_e32 v160, v160
	v_exp_f32_e32 v161, v161
	v_exp_f32_e32 v162, v162
	v_exp_f32_e32 v163, v163
	s_nop 0
	v_add_f32_e32 v160, 1.0, v160
	v_add_f32_e32 v161, 1.0, v161
	v_add_f32_e32 v162, 1.0, v162
	v_add_f32_e32 v163, 1.0, v163
	v_rcp_f32_e32 v160, v160
	v_rcp_f32_e32 v161, v161
	v_rcp_f32_e32 v162, v162
	v_rcp_f32_e32 v163, v163
	s_nop 0
	v_pk_mul_f32 v[160:161], v[88:89], v[160:161]
	v_pk_mul_f32 v[162:163], v[90:91], v[162:163]
	v_pk_mul_f32 v[160:161], v[92:93], v[160:161]
	v_pk_mul_f32 v[162:163], v[94:95], v[162:163]
	v_cvt_pk_bf16_f32 v160, v160, v161
	v_cvt_pk_bf16_f32 v161, v162, v163
	v_mul_f32_e32 v164, 0xbfb8aa3b, v96
	v_mul_f32_e32 v165, 0xbfb8aa3b, v97
	v_mul_f32_e32 v166, 0xbfb8aa3b, v98
	v_mul_f32_e32 v167, 0xbfb8aa3b, v99
	v_exp_f32_e32 v164, v164
	v_exp_f32_e32 v165, v165
	v_exp_f32_e32 v166, v166
	v_exp_f32_e32 v167, v167
	s_nop 0
	v_add_f32_e32 v164, 1.0, v164
	v_add_f32_e32 v165, 1.0, v165
	v_add_f32_e32 v166, 1.0, v166
	v_add_f32_e32 v167, 1.0, v167
	v_rcp_f32_e32 v164, v164
	v_rcp_f32_e32 v165, v165
	v_rcp_f32_e32 v166, v166
	v_rcp_f32_e32 v167, v167
	s_nop 0
	v_pk_mul_f32 v[164:165], v[96:97], v[164:165]
	v_pk_mul_f32 v[166:167], v[98:99], v[166:167]
	v_pk_mul_f32 v[164:165], v[100:101], v[164:165]
	v_pk_mul_f32 v[166:167], v[102:103], v[166:167]
	v_cvt_pk_bf16_f32 v162, v164, v165
	v_cvt_pk_bf16_f32 v163, v166, v167
	s_nop 1
	v_permlane16_swap_b32_e32 v160, v162
	v_permlane16_swap_b32_e32 v161, v163
	global_store_dwordx4 v237, v[160:163], s[2:3] offset:0
	v_mul_f32_e32 v168, 0xbfb8aa3b, v120
	v_mul_f32_e32 v169, 0xbfb8aa3b, v121
	v_mul_f32_e32 v170, 0xbfb8aa3b, v122
	v_mul_f32_e32 v171, 0xbfb8aa3b, v123
	v_exp_f32_e32 v168, v168
	v_exp_f32_e32 v169, v169
	v_exp_f32_e32 v170, v170
	v_exp_f32_e32 v171, v171
	s_nop 0
	v_add_f32_e32 v168, 1.0, v168
	v_add_f32_e32 v169, 1.0, v169
	v_add_f32_e32 v170, 1.0, v170
	v_add_f32_e32 v171, 1.0, v171
	v_rcp_f32_e32 v168, v168
	v_rcp_f32_e32 v169, v169
	v_rcp_f32_e32 v170, v170
	v_rcp_f32_e32 v171, v171
	s_nop 0
	v_pk_mul_f32 v[168:169], v[120:121], v[168:169]
	v_pk_mul_f32 v[170:171], v[122:123], v[170:171]
	v_pk_mul_f32 v[168:169], v[124:125], v[168:169]
	v_pk_mul_f32 v[170:171], v[126:127], v[170:171]
	v_cvt_pk_bf16_f32 v168, v168, v169
	v_cvt_pk_bf16_f32 v169, v170, v171
	v_mul_f32_e32 v172, 0xbfb8aa3b, v128
	v_mul_f32_e32 v173, 0xbfb8aa3b, v129
	v_mul_f32_e32 v174, 0xbfb8aa3b, v130
	v_mul_f32_e32 v175, 0xbfb8aa3b, v131
	v_exp_f32_e32 v172, v172
	v_exp_f32_e32 v173, v173
	v_exp_f32_e32 v174, v174
	v_exp_f32_e32 v175, v175
	s_nop 0
	v_add_f32_e32 v172, 1.0, v172
	v_add_f32_e32 v173, 1.0, v173
	v_add_f32_e32 v174, 1.0, v174
	v_add_f32_e32 v175, 1.0, v175
	v_rcp_f32_e32 v172, v172
	v_rcp_f32_e32 v173, v173
	v_rcp_f32_e32 v174, v174
	v_rcp_f32_e32 v175, v175
	s_nop 0
	v_pk_mul_f32 v[172:173], v[128:129], v[172:173]
	v_pk_mul_f32 v[174:175], v[130:131], v[174:175]
	v_pk_mul_f32 v[172:173], v[132:133], v[172:173]
	v_pk_mul_f32 v[174:175], v[134:135], v[174:175]
	v_cvt_pk_bf16_f32 v170, v172, v173
	v_cvt_pk_bf16_f32 v171, v174, v175
	s_nop 1
	v_permlane16_swap_b32_e32 v168, v170
	v_permlane16_swap_b32_e32 v169, v171
	global_store_dwordx4 v237, v[168:171], s[2:3] offset:128
	s_add_u32 s2, s2, 0x2c000
	s_addc_u32 s3, s3, 0
	v_mul_f32_e32 v152, 0xbfb8aa3b, v104
	v_mul_f32_e32 v153, 0xbfb8aa3b, v105
	v_mul_f32_e32 v154, 0xbfb8aa3b, v106
	v_mul_f32_e32 v155, 0xbfb8aa3b, v107
	v_exp_f32_e32 v152, v152
	v_exp_f32_e32 v153, v153
	v_exp_f32_e32 v154, v154
	v_exp_f32_e32 v155, v155
	s_nop 0
	v_add_f32_e32 v152, 1.0, v152
	v_add_f32_e32 v153, 1.0, v153
	v_add_f32_e32 v154, 1.0, v154
	v_add_f32_e32 v155, 1.0, v155
	v_rcp_f32_e32 v152, v152
	v_rcp_f32_e32 v153, v153
	v_rcp_f32_e32 v154, v154
	v_rcp_f32_e32 v155, v155
	s_nop 0
	v_pk_mul_f32 v[152:153], v[104:105], v[152:153]
	v_pk_mul_f32 v[154:155], v[106:107], v[154:155]
	v_pk_mul_f32 v[152:153], v[108:109], v[152:153]
	v_pk_mul_f32 v[154:155], v[110:111], v[154:155]
	v_cvt_pk_bf16_f32 v152, v152, v153
	v_cvt_pk_bf16_f32 v153, v154, v155
	v_mul_f32_e32 v156, 0xbfb8aa3b, v112
	v_mul_f32_e32 v157, 0xbfb8aa3b, v113
	v_mul_f32_e32 v158, 0xbfb8aa3b, v114
	v_mul_f32_e32 v159, 0xbfb8aa3b, v115
	v_exp_f32_e32 v156, v156
	v_exp_f32_e32 v157, v157
; #define LAS __attribute__((address_space(3)))
; DI void gemm_stream2(const bf16_t* __restrict__ A, int lda, const bf16_t* __restrict__ Bt, int ldb, int K, int m0, int n0, ...
;     ...
;     for (int kt = 0; kt < nk; ++kt) {
;         const bool pf = (kt + 2 < nk) || has_next, more = (kt + 1 < nk) || has_next;
;         const bf16_t* pa = (kt + 2 < nk) ? ga + (kt + 2) * 64 : gan + (kt + 2 - nk) * 64;
;         const bf16_t* pb = (kt + 2 < nk) ? gb + (kt + 2) * 64 : gbn + (kt + 2 - nk) * 64;
;         const int plda = (kt + 2 < nk) ? lda : ldan, pldb = (kt + 2 < nk) ? ldb : ldbn;
;         const int s2 = st >= 1 ? st - 1 : 2;
;         const LAS char* base = lds + st * 49152;
; #pragma unroll
;         for (int ks = 0; ks < 2; ++ks) {
;             const unsigned fo = ks ? fo1 : fo0;
;             bf16x8 af[4], bfr[4];
; #pragma unroll
;             for (int i = 0; i < 4; ++i) { af[i] = *(const LAS bf16x8*)(base + aoff + i * 2048 + fo); bfr[i] = *(const LAS bf16x8*)(base + boff + i * 2048 + fo); }
;     DI bool next(int& tm, int& tn) {
;         if (L >= end) return false;
;         const int gsz = 8 * ntn, grp = L / gsz, rem = L - grp * gsz, rows = min(8, ntm - grp * 8);
;         tn = rem / rows; tm = grp * 8 + (rem - tn * rows);
;         L += step; return true;
;     }
; DI void zero_acc(f32x4 (&acc)[4][4]) {
; #pragma unroll
;     for (int i = 0; i < 4; ++i)
; #pragma unroll
;         for (int j = 0; j < 4; ++j) acc[i][j] = (f32x4){0.f, 0.f, 0.f, 0.f};
; }
; DI void gemm_gu(const Params& p, size_t woff, int bid, int nb, char* smem, const int tid) {
;     const bf16_t* A = (const bf16_t*)(p.ws + B_XN);
;     const bf16_t* Bt = (const bf16_t*)(p.ws + woff);
;     bf16_t* ACT = (bf16_t*)(p.ws + B_ACT);
;     const int ntn = 44, ntiles = 130 * ntn;
;     const int lane = tid & 63, wave = __builtin_amdgcn_readfirstlane(tid >> 6), wm = wave >> 1, wn = wave & 1, r = lane & 15, q = lane >> 4;
;     TileIter ti; ti.init(65, ntn, bid, nb);
;     int tm, tn, tm2 = 0, tn2 = 0;
;     bool have = ti.next(tm, tn);
;     Ring rg; rg.st = 0; rg.primed = 0;
;     for (; have; tm = tm2, tn = tn2) {
;         have = ti.next(tm2, tn2);
;         const int m0 = tm * 256, n0 = tn * 128;
;         f32x4 acc[4][4]; zero_acc(acc);
;         gemm_stream(A, 1024, Bt, 1024, 1024, m0, n0, have, tm2 * 256, tn2 * 128, smem, acc, tid, rg);
	v_exp_f32_e32 v158, v158
	v_exp_f32_e32 v159, v159
	s_nop 0
	v_add_f32_e32 v156, 1.0, v156
	v_add_f32_e32 v157, 1.0, v157
	v_add_f32_e32 v158, 1.0, v158
	v_add_f32_e32 v159, 1.0, v159
	v_rcp_f32_e32 v156, v156
	v_rcp_f32_e32 v157, v157
	v_rcp_f32_e32 v158, v158
	v_rcp_f32_e32 v159, v159
	s_nop 0
	v_pk_mul_f32 v[156:157], v[112:113], v[156:157]
	v_pk_mul_f32 v[158:159], v[114:115], v[158:159]
	v_pk_mul_f32 v[156:157], v[116:117], v[156:157]
	v_pk_mul_f32 v[158:159], v[118:119], v[158:159]
	v_cvt_pk_bf16_f32 v154, v156, v157
	v_cvt_pk_bf16_f32 v155, v158, v159
	s_nop 1
	v_permlane16_swap_b32_e32 v152, v154
	v_permlane16_swap_b32_e32 v153, v155
	global_store_dwordx4 v237, v[152:155], s[2:3] offset:0
	v_mul_f32_e32 v160, 0xbfb8aa3b, v136
	v_mul_f32_e32 v161, 0xbfb8aa3b, v137
	v_mul_f32_e32 v162, 0xbfb8aa3b, v138
	v_mul_f32_e32 v163, 0xbfb8aa3b, v139
	v_exp_f32_e32 v160, v160
	v_exp_f32_e32 v161, v161
	v_exp_f32_e32 v162, v162
	v_exp_f32_e32 v163, v163
	s_nop 0
	v_add_f32_e32 v160, 1.0, v160
	v_add_f32_e32 v161, 1.0, v161
	v_add_f32_e32 v162, 1.0, v162
	v_add_f32_e32 v163, 1.0, v163
	v_rcp_f32_e32 v160, v160
	v_rcp_f32_e32 v161, v161
	v_rcp_f32_e32 v162, v162
	v_rcp_f32_e32 v163, v163
	s_nop 0
	v_pk_mul_f32 v[160:161], v[136:137], v[160:161]
	v_pk_mul_f32 v[162:163], v[138:139], v[162:163]
	v_pk_mul_f32 v[160:161], v[140:141], v[160:161]
	v_pk_mul_f32 v[162:163], v[142:143], v[162:163]
	v_cvt_pk_bf16_f32 v160, v160, v161
	v_cvt_pk_bf16_f32 v161, v162, v163
	v_mul_f32_e32 v164, 0xbfb8aa3b, v144
	v_mul_f32_e32 v165, 0xbfb8aa3b, v145
	v_mul_f32_e32 v166, 0xbfb8aa3b, v146
	v_mul_f32_e32 v167, 0xbfb8aa3b, v147
	v_exp_f32_e32 v164, v164
	v_exp_f32_e32 v165, v165
	v_exp_f32_e32 v166, v166
	v_exp_f32_e32 v167, v167
	s_nop 0
	v_add_f32_e32 v164, 1.0, v164
	v_add_f32_e32 v165, 1.0, v165
	v_add_f32_e32 v166, 1.0, v166
	v_add_f32_e32 v167, 1.0, v167
	v_rcp_f32_e32 v164, v164
	v_rcp_f32_e32 v165, v165
	v_rcp_f32_e32 v166, v166
	v_rcp_f32_e32 v167, v167
	s_nop 0
	v_pk_mul_f32 v[164:165], v[144:145], v[164:165]
	v_pk_mul_f32 v[166:167], v[146:147], v[166:167]
	v_pk_mul_f32 v[164:165], v[148:149], v[164:165]
	v_pk_mul_f32 v[166:167], v[150:151], v[166:167]
	v_cvt_pk_bf16_f32 v162, v164, v165
	v_cvt_pk_bf16_f32 v163, v166, v167
	s_nop 1
	v_permlane16_swap_b32_e32 v160, v162
	v_permlane16_swap_b32_e32 v161, v163
	global_store_dwordx4 v237, v[160:163], s[2:3] offset:128
	s_cmp_eq_u32 s54, 0
	s_cbranch_scc1 .LBB0_860
	s_mov_b32 s51, s76
	s_mov_b32 s57, s59
	s_mov_b32 s58, s60
	s_add_u32 s76, s51, s53
	s_cmp_lt_u32 s76, s52
	s_cselect_b32 s54, 1, 0
	s_cbranch_scc0 .Lgu_nonext2
	s_mul_i32 s1, s76, 0x1745e
	s_lshr_b32 s2, s1, 24
	s_mul_i32 s1, s2, 0xb0
	s_sub_u32 s1, s76, s1
	s_lshr_b32 s3, s1, 3
	s_and_b32 s37, s1, 7
	s_cmp_lt_u32 s2, 8
	s_cselect_b32 s60, s3, s1
	s_cselect_b32 s37, s37, 0
	s_lshl_b32 s2, s2, 3
	s_add_i32 s59, s2, s37
	s_lshl_b32 s1, s59, 19
	s_lshl_b32 s2, s10, 15
	s_add_u32 s1, s1, s2
	s_add_u32 s1, s1, 0x3240000
	s_add_u32 s74, s88, s1
	s_addc_u32 s75, s89, 0
	s_add_u32 s78, s74, 0x40000
	s_addc_u32 s79, s75, 0
	s_lshl_b32 s1, s60, 19
	s_add_u32 s1, s1, s2
	s_add_u32 s1, s1, s61
	s_add_u32 s80, s88, s1
	s_addc_u32 s81, s89, 0
	s_add_u32 s82, s80, 0x40000
	s_addc_u32 s83, s81, 0
.Lgu_nonext2:
	v_mov_b64_e32 v[24:25], 0
	v_mov_b64_e32 v[26:27], 0
	v_mov_b64_e32 v[28:29], 0
	v_mov_b64_e32 v[30:31], 0
	v_mov_b64_e32 v[32:33], 0
	v_mov_b64_e32 v[34:35], 0
	v_mov_b64_e32 v[36:37], 0
	v_mov_b64_e32 v[38:39], 0
	v_mov_b64_e32 v[40:41], 0
	v_mov_b64_e32 v[42:43], 0
	v_mov_b64_e32 v[44:45], 0
	v_mov_b64_e32 v[46:47], 0
	v_mov_b64_e32 v[48:49], 0
	v_mov_b64_e32 v[50:51], 0
	v_mov_b64_e32 v[52:53], 0
	v_mov_b64_e32 v[54:55], 0
	v_mov_b64_e32 v[56:57], 0
	v_mov_b64_e32 v[58:59], 0
	v_mov_b64_e32 v[60:61], 0
	v_mov_b64_e32 v[62:63], 0
	v_mov_b64_e32 v[64:65], 0
	v_mov_b64_e32 v[66:67], 0
	v_mov_b64_e32 v[68:69], 0
	v_mov_b64_e32 v[70:71], 0
	v_mov_b64_e32 v[72:73], 0
	v_mov_b64_e32 v[74:75], 0
	v_mov_b64_e32 v[76:77], 0
	v_mov_b64_e32 v[78:79], 0
	v_mov_b64_e32 v[80:81], 0
	v_mov_b64_e32 v[82:83], 0
	v_mov_b64_e32 v[84:85], 0
	v_mov_b64_e32 v[86:87], 0
	v_mov_b64_e32 v[88:89], 0
	v_mov_b64_e32 v[90:91], 0
	v_mov_b64_e32 v[92:93], 0
	v_mov_b64_e32 v[94:95], 0
	v_mov_b64_e32 v[96:97], 0
	v_mov_b64_e32 v[98:99], 0
	v_mov_b64_e32 v[100:101], 0
	v_mov_b64_e32 v[102:103], 0
	v_mov_b64_e32 v[104:105], 0
	v_mov_b64_e32 v[106:107], 0
	v_mov_b64_e32 v[108:109], 0
	v_mov_b64_e32 v[110:111], 0
	v_mov_b64_e32 v[112:113], 0
	v_mov_b64_e32 v[114:115], 0
	v_mov_b64_e32 v[116:117], 0
	v_mov_b64_e32 v[118:119], 0
	v_mov_b64_e32 v[120:121], 0
	v_mov_b64_e32 v[122:123], 0
	v_mov_b64_e32 v[124:125], 0
	v_mov_b64_e32 v[126:127], 0
	v_mov_b64_e32 v[128:129], 0
	v_mov_b64_e32 v[130:131], 0
	v_mov_b64_e32 v[132:133], 0
	v_mov_b64_e32 v[134:135], 0
	v_mov_b64_e32 v[136:137], 0
	v_mov_b64_e32 v[138:139], 0
	v_mov_b64_e32 v[140:141], 0
	v_mov_b64_e32 v[142:143], 0
	v_mov_b64_e32 v[144:145], 0
	v_mov_b64_e32 v[146:147], 0
	v_mov_b64_e32 v[148:149], 0
	v_mov_b64_e32 v[150:151], 0
	s_add_u32 s0, s54, 7
	ds_read_b128 v[0:3], v188 offset:16
	ds_read_b128 v[4:7], v189 offset:16
	ds_read_b128 v[8:11], v188 offset:2064
	ds_read_b128 v[12:15], v189 offset:2064
	ds_read_b128 v[196:199], v188 offset:16400
	ds_read_b128 v[200:203], v189 offset:16400
	ds_read_b128 v[204:207], v188 offset:18448
	ds_read_b128 v[208:211], v189 offset:18448
	ds_read_b128 v[152:155], v186 offset:16
	ds_read_b128 v[156:159], v187 offset:16
	ds_read_b128 v[160:163], v186 offset:2064
	ds_read_b128 v[164:167], v187 offset:2064
	ds_read_b128 v[168:171], v186 offset:4112
	ds_read_b128 v[172:175], v187 offset:4112
	ds_read_b128 v[176:179], v186 offset:6160
	ds_read_b128 v[180:183], v187 offset:6160
	s_add_i32 m0, s39, 0xc000
	s_nop 0
	global_load_lds_dwordx4 v184, s[68:69]
	s_add_i32 m0, s39, 0xc400
	s_nop 0
	global_load_lds_dwordx4 v185, s[68:69]
	s_add_u32 s68, s68, 0x80
	s_addc_u32 s69, s69, 0
	s_waitcnt lgkmcnt(0)
	s_waitcnt vmcnt(16)
	s_barrier
; #define LAS __attribute__((address_space(3)))
; #define BAR() { __builtin_amdgcn_sched_barrier(0); __builtin_amdgcn_s_barrier(); asm volatile("" ::: "memory"); __builtin_amdgcn_sched_barrier(0); }
; DI void gemm_stream2(const bf16_t* __restrict__ A, int lda, const bf16_t* __restrict__ Bt, int ldb, int K, int m0, int n0, ...
;     ...
;     for (int kt = 0; kt < nk; ++kt) {
;         const bool pf = (kt + 2 < nk) || has_next, more = (kt + 1 < nk) || has_next;
;         const bf16_t* pa = (kt + 2 < nk) ? ga + (kt + 2) * 64 : gan + (kt + 2 - nk) * 64;
;         const bf16_t* pb = (kt + 2 < nk) ? gb + (kt + 2) * 64 : gbn + (kt + 2 - nk) * 64;
;         const int plda = (kt + 2 < nk) ? lda : ldan, pldb = (kt + 2 < nk) ? ldb : ldbn;
;         const int s2 = st >= 1 ? st - 1 : 2;
;         const LAS char* base = lds + st * 49152;
; #pragma unroll
;         for (int ks = 0; ks < 2; ++ks) {
;             const unsigned fo = ks ? fo1 : fo0;
;             bf16x8 af[4], bfr[4];
; #pragma unroll
;             for (int i = 0; i < 4; ++i) { af[i] = *(const LAS bf16x8*)(base + aoff + i * 2048 + fo); bfr[i] = *(const LAS bf16x8*)(base + boff + i * 2048 + fo); }
;             if (ks == 1 && more) { if (pf) asm volatile("s_waitcnt vmcnt(3)" ::: "memory"); else asm volatile("s_waitcnt vmcnt(0)" ::: "memory"); }
;             if (pf) { PIECE(s2, ks * 3 + 0); PIECE(s2, ks * 3 + 1); PIECE(s2, ks * 3 + 2); }
;             asm volatile("s_waitcnt lgkmcnt(0)" ::: "memory");
;             BAR();
;             __builtin_amdgcn_s_setprio(1);
; #pragma unroll
;             for (int mi = 0; mi < 4; ++mi)
; #pragma unroll
;                 for (int ni = 0; ni < 4; ++ni) acc[mi][ni] = __builtin_amdgcn_mfma_f32_16x16x32_bf16(bfr[ni], af[mi], acc[mi][ni], 0, 0, 0);
;             __builtin_amdgcn_s_setprio(0);
;             BAR();
;         }
	s_setprio 1
	v_mfma_f32_16x16x32_bf16 v[24:27], v[0:3], v[152:155], v[24:27]
	v_mfma_f32_16x16x32_bf16 v[28:31], v[8:11], v[152:155], v[28:31]
	v_mfma_f32_16x16x32_bf16 v[32:35], v[0:3], v[160:163], v[32:35]
	v_mfma_f32_16x16x32_bf16 v[36:39], v[8:11], v[160:163], v[36:39]
	v_mfma_f32_16x16x32_bf16 v[40:43], v[0:3], v[168:171], v[40:43]
	v_mfma_f32_16x16x32_bf16 v[44:47], v[8:11], v[168:171], v[44:47]
	v_mfma_f32_16x16x32_bf16 v[48:51], v[0:3], v[176:179], v[48:51]
	v_mfma_f32_16x16x32_bf16 v[52:55], v[8:11], v[176:179], v[52:55]
	v_mfma_f32_16x16x32_bf16 v[24:27], v[4:7], v[156:159], v[24:27]
	v_mfma_f32_16x16x32_bf16 v[28:31], v[12:15], v[156:159], v[28:31]
	v_mfma_f32_16x16x32_bf16 v[32:35], v[4:7], v[164:167], v[32:35]
	v_mfma_f32_16x16x32_bf16 v[36:39], v[12:15], v[164:167], v[36:39]
	v_mfma_f32_16x16x32_bf16 v[40:43], v[4:7], v[172:175], v[40:43]
	v_mfma_f32_16x16x32_bf16 v[44:47], v[12:15], v[172:175], v[44:47]
	v_mfma_f32_16x16x32_bf16 v[48:51], v[4:7], v[180:183], v[48:51]
	v_mfma_f32_16x16x32_bf16 v[52:55], v[12:15], v[180:183], v[52:55]
	v_mfma_f32_16x16x32_bf16 v[56:59], v[196:199], v[152:155], v[56:59]
	v_mfma_f32_16x16x32_bf16 v[60:63], v[204:207], v[152:155], v[60:63]
	v_mfma_f32_16x16x32_bf16 v[64:67], v[196:199], v[160:163], v[64:67]
	v_mfma_f32_16x16x32_bf16 v[68:71], v[204:207], v[160:163], v[68:71]
	v_mfma_f32_16x16x32_bf16 v[72:75], v[196:199], v[168:171], v[72:75]
	v_mfma_f32_16x16x32_bf16 v[76:79], v[204:207], v[168:171], v[76:79]
	v_mfma_f32_16x16x32_bf16 v[80:83], v[196:199], v[176:179], v[80:83]
	v_mfma_f32_16x16x32_bf16 v[84:87], v[204:207], v[176:179], v[84:87]
	v_mfma_f32_16x16x32_bf16 v[56:59], v[200:203], v[156:159], v[56:59]
	v_mfma_f32_16x16x32_bf16 v[60:63], v[208:211], v[156:159], v[60:63]
	v_mfma_f32_16x16x32_bf16 v[64:67], v[200:203], v[164:167], v[64:67]
	v_mfma_f32_16x16x32_bf16 v[68:71], v[208:211], v[164:167], v[68:71]
	v_mfma_f32_16x16x32_bf16 v[72:75], v[200:203], v[172:175], v[72:75]
	v_mfma_f32_16x16x32_bf16 v[76:79], v[208:211], v[172:175], v[76:79]
	v_mfma_f32_16x16x32_bf16 v[80:83], v[200:203], v[180:183], v[80:83]
	v_mfma_f32_16x16x32_bf16 v[84:87], v[208:211], v[180:183], v[84:87]
	s_setprio 0
	s_barrier
	ds_read_b128 v[152:155], v186 offset:16400
	ds_read_b128 v[156:159], v187 offset:16400
	ds_read_b128 v[160:163], v186 offset:18448
	ds_read_b128 v[164:167], v187 offset:18448
	ds_read_b128 v[168:171], v186 offset:20496
	ds_read_b128 v[172:175], v187 offset:20496
	ds_read_b128 v[176:179], v186 offset:22544
	ds_read_b128 v[180:183], v187 offset:22544
	s_cmp_lg_u32 s0, s54
	s_cbranch_scc1 .Lgu_nosw3
	s_mov_b64 s[66:67], s[74:75]
	s_mov_b64 s[70:71], s[80:81]
	s_mov_b64 s[72:73], s[82:83]
.Lgu_nosw3:
	s_add_i32 m0, s39, 0x10000
	s_nop 0
	global_load_lds_dwordx4 v184, s[70:71]
	s_add_i32 m0, s39, 0x10400
	s_nop 0
	global_load_lds_dwordx4 v185, s[70:71]
	s_add_u32 s70, s70, 0x80
	s_addc_u32 s71, s71, 0
	s_add_i32 m0, s39, 0x0
	s_nop 0
	global_load_lds_dwordx4 v184, s[66:67]
	s_add_i32 m0, s39, 0x400
	s_nop 0
	global_load_lds_dwordx4 v185, s[66:67]
	s_add_u32 s66, s66, 0x80
	s_addc_u32 s67, s67, 0
	s_add_i32 m0, s39, 0x14000
	s_nop 0
	global_load_lds_dwordx4 v184, s[72:73]
	s_add_i32 m0, s39, 0x14400
	s_nop 0
	global_load_lds_dwordx4 v185, s[72:73]
	s_add_u32 s72, s72, 0x80
	s_addc_u32 s73, s73, 0
	s_waitcnt lgkmcnt(0)
	s_waitcnt vmcnt(16)
	s_barrier
	s_setprio 1
	v_mfma_f32_16x16x32_bf16 v[88:91], v[0:3], v[152:155], v[88:91]
	v_mfma_f32_16x16x32_bf16 v[92:95], v[8:11], v[152:155], v[92:95]
	v_mfma_f32_16x16x32_bf16 v[96:99], v[0:3], v[160:163], v[96:99]
	v_mfma_f32_16x16x32_bf16 v[100:103], v[8:11], v[160:163], v[100:103]
	v_mfma_f32_16x16x32_bf16 v[104:107], v[0:3], v[168:171], v[104:107]
	v_mfma_f32_16x16x32_bf16 v[108:111], v[8:11], v[168:171], v[108:111]
	v_mfma_f32_16x16x32_bf16 v[112:115], v[0:3], v[176:179], v[112:115]
	v_mfma_f32_16x16x32_bf16 v[116:119], v[8:11], v[176:179], v[116:119]
	v_mfma_f32_16x16x32_bf16 v[88:91], v[4:7], v[156:159], v[88:91]
	v_mfma_f32_16x16x32_bf16 v[92:95], v[12:15], v[156:159], v[92:95]
	v_mfma_f32_16x16x32_bf16 v[96:99], v[4:7], v[164:167], v[96:99]
	v_mfma_f32_16x16x32_bf16 v[100:103], v[12:15], v[164:167], v[100:103]
	v_mfma_f32_16x16x32_bf16 v[104:107], v[4:7], v[172:175], v[104:107]
	v_mfma_f32_16x16x32_bf16 v[108:111], v[12:15], v[172:175], v[108:111]
	v_mfma_f32_16x16x32_bf16 v[112:115], v[4:7], v[180:183], v[112:115]
	v_mfma_f32_16x16x32_bf16 v[116:119], v[12:15], v[180:183], v[116:119]
	v_mfma_f32_16x16x32_bf16 v[120:123], v[196:199], v[152:155], v[120:123]
	v_mfma_f32_16x16x32_bf16 v[124:127], v[204:207], v[152:155], v[124:127]
	v_mfma_f32_16x16x32_bf16 v[128:131], v[196:199], v[160:163], v[128:131]
	v_mfma_f32_16x16x32_bf16 v[132:135], v[204:207], v[160:163], v[132:135]
	v_mfma_f32_16x16x32_bf16 v[136:139], v[196:199], v[168:171], v[136:139]
	v_mfma_f32_16x16x32_bf16 v[140:143], v[204:207], v[168:171], v[140:143]
	v_mfma_f32_16x16x32_bf16 v[144:147], v[196:199], v[176:179], v[144:147]
	v_mfma_f32_16x16x32_bf16 v[148:151], v[204:207], v[176:179], v[148:151]
	v_mfma_f32_16x16x32_bf16 v[120:123], v[200:203], v[156:159], v[120:123]
	v_mfma_f32_16x16x32_bf16 v[124:127], v[208:211], v[156:159], v[124:127]
	v_mfma_f32_16x16x32_bf16 v[128:131], v[200:203], v[164:167], v[128:131]
	v_mfma_f32_16x16x32_bf16 v[132:135], v[208:211], v[164:167], v[132:135]
	v_mfma_f32_16x16x32_bf16 v[136:139], v[200:203], v[172:175], v[136:139]
	v_mfma_f32_16x16x32_bf16 v[140:143], v[208:211], v[172:175], v[140:143]
	v_mfma_f32_16x16x32_bf16 v[144:147], v[200:203], v[180:183], v[144:147]
	v_mfma_f32_16x16x32_bf16 v[148:151], v[208:211], v[180:183], v[148:151]
	s_setprio 0
	s_barrier
	ds_read_b128 v[0:3], v188 offset:32784
	ds_read_b128 v[4:7], v189 offset:32784
	ds_read_b128 v[8:11], v188 offset:34832
	ds_read_b128 v[12:15], v189 offset:34832
	ds_read_b128 v[196:199], v188 offset:49168
	ds_read_b128 v[200:203], v189 offset:49168
	ds_read_b128 v[204:207], v188 offset:51216
	ds_read_b128 v[208:211], v189 offset:51216
	ds_read_b128 v[152:155], v186 offset:32784
	ds_read_b128 v[156:159], v187 offset:32784
	ds_read_b128 v[160:163], v186 offset:34832
	ds_read_b128 v[164:167], v187 offset:34832
	ds_read_b128 v[168:171], v186 offset:36880
	ds_read_b128 v[172:175], v187 offset:36880
	ds_read_b128 v[176:179], v186 offset:38928
	ds_read_b128 v[180:183], v187 offset:38928
	s_cmp_lg_u32 s0, s54
	s_cbranch_scc1 .Lgu_nosw4
	s_mov_b64 s[68:69], s[78:79]
; #define LAS __attribute__((address_space(3)))
; #define BAR() { __builtin_amdgcn_sched_barrier(0); __builtin_amdgcn_s_barrier(); asm volatile("" ::: "memory"); __builtin_amdgcn_sched_barrier(0); }
; DI void gemm_stream2(const bf16_t* __restrict__ A, int lda, const bf16_t* __restrict__ Bt, int ldb, int K, int m0, int n0, ...
;     ...
;     for (int kt = 0; kt < nk; ++kt) {
;         const bool pf = (kt + 2 < nk) || has_next, more = (kt + 1 < nk) || has_next;
;         const bf16_t* pa = (kt + 2 < nk) ? ga + (kt + 2) * 64 : gan + (kt + 2 - nk) * 64;
;         const bf16_t* pb = (kt + 2 < nk) ? gb + (kt + 2) * 64 : gbn + (kt + 2 - nk) * 64;
;         const int plda = (kt + 2 < nk) ? lda : ldan, pldb = (kt + 2 < nk) ? ldb : ldbn;
;         const int s2 = st >= 1 ? st - 1 : 2;
;         const LAS char* base = lds + st * 49152;
; #pragma unroll
;         for (int ks = 0; ks < 2; ++ks) {
;             const unsigned fo = ks ? fo1 : fo0;
;             bf16x8 af[4], bfr[4];
; #pragma unroll
;             for (int i = 0; i < 4; ++i) { af[i] = *(const LAS bf16x8*)(base + aoff + i * 2048 + fo); bfr[i] = *(const LAS bf16x8*)(base + boff + i * 2048 + fo); }
;             if (ks == 1 && more) { if (pf) asm volatile("s_waitcnt vmcnt(3)" ::: "memory"); else asm volatile("s_waitcnt vmcnt(0)" ::: "memory"); }
;             if (pf) { PIECE(s2, ks * 3 + 0); PIECE(s2, ks * 3 + 1); PIECE(s2, ks * 3 + 2); }
;             asm volatile("s_waitcnt lgkmcnt(0)" ::: "memory");
;             BAR();
;             __builtin_amdgcn_s_setprio(1);
; #pragma unroll
;             for (int mi = 0; mi < 4; ++mi)
; #pragma unroll
;                 for (int ni = 0; ni < 4; ++ni) acc[mi][ni] = __builtin_amdgcn_mfma_f32_16x16x32_bf16(bfr[ni], af[mi], acc[mi][ni], 0, 0, 0);
;             __builtin_amdgcn_s_setprio(0);
;             BAR();
;         }
.Lgu_nosw4:
	s_add_i32 m0, s39, 0x4000
	s_nop 0
	global_load_lds_dwordx4 v184, s[68:69]
	s_add_i32 m0, s39, 0x4400
	s_nop 0
	global_load_lds_dwordx4 v185, s[68:69]
	s_add_u32 s68, s68, 0x80
	s_addc_u32 s69, s69, 0
	s_waitcnt lgkmcnt(0)
	s_waitcnt vmcnt(8)
	s_barrier
	s_setprio 1
	v_mfma_f32_16x16x32_bf16 v[24:27], v[0:3], v[152:155], v[24:27]
	v_mfma_f32_16x16x32_bf16 v[28:31], v[8:11], v[152:155], v[28:31]
	v_mfma_f32_16x16x32_bf16 v[32:35], v[0:3], v[160:163], v[32:35]
	v_mfma_f32_16x16x32_bf16 v[36:39], v[8:11], v[160:163], v[36:39]
	v_mfma_f32_16x16x32_bf16 v[40:43], v[0:3], v[168:171], v[40:43]
	v_mfma_f32_16x16x32_bf16 v[44:47], v[8:11], v[168:171], v[44:47]
	v_mfma_f32_16x16x32_bf16 v[48:51], v[0:3], v[176:179], v[48:51]
	v_mfma_f32_16x16x32_bf16 v[52:55], v[8:11], v[176:179], v[52:55]
	v_mfma_f32_16x16x32_bf16 v[24:27], v[4:7], v[156:159], v[24:27]
	v_mfma_f32_16x16x32_bf16 v[28:31], v[12:15], v[156:159], v[28:31]
	v_mfma_f32_16x16x32_bf16 v[32:35], v[4:7], v[164:167], v[32:35]
	v_mfma_f32_16x16x32_bf16 v[36:39], v[12:15], v[164:167], v[36:39]
	v_mfma_f32_16x16x32_bf16 v[40:43], v[4:7], v[172:175], v[40:43]
	v_mfma_f32_16x16x32_bf16 v[44:47], v[12:15], v[172:175], v[44:47]
	v_mfma_f32_16x16x32_bf16 v[48:51], v[4:7], v[180:183], v[48:51]
	v_mfma_f32_16x16x32_bf16 v[52:55], v[12:15], v[180:183], v[52:55]
	v_mfma_f32_16x16x32_bf16 v[56:59], v[196:199], v[152:155], v[56:59]
	v_mfma_f32_16x16x32_bf16 v[60:63], v[204:207], v[152:155], v[60:63]
	v_mfma_f32_16x16x32_bf16 v[64:67], v[196:199], v[160:163], v[64:67]
	v_mfma_f32_16x16x32_bf16 v[68:71], v[204:207], v[160:163], v[68:71]
	v_mfma_f32_16x16x32_bf16 v[72:75], v[196:199], v[168:171], v[72:75]
	v_mfma_f32_16x16x32_bf16 v[76:79], v[204:207], v[168:171], v[76:79]
	v_mfma_f32_16x16x32_bf16 v[80:83], v[196:199], v[176:179], v[80:83]
	v_mfma_f32_16x16x32_bf16 v[84:87], v[204:207], v[176:179], v[84:87]
	v_mfma_f32_16x16x32_bf16 v[56:59], v[200:203], v[156:159], v[56:59]
	v_mfma_f32_16x16x32_bf16 v[60:63], v[208:211], v[156:159], v[60:63]
	v_mfma_f32_16x16x32_bf16 v[64:67], v[200:203], v[164:167], v[64:67]
	v_mfma_f32_16x16x32_bf16 v[68:71], v[208:211], v[164:167], v[68:71]
	v_mfma_f32_16x16x32_bf16 v[72:75], v[200:203], v[172:175], v[72:75]
	v_mfma_f32_16x16x32_bf16 v[76:79], v[208:211], v[172:175], v[76:79]
	v_mfma_f32_16x16x32_bf16 v[80:83], v[200:203], v[180:183], v[80:83]
	v_mfma_f32_16x16x32_bf16 v[84:87], v[208:211], v[180:183], v[84:87]
	s_setprio 0
	s_barrier
	ds_read_b128 v[152:155], v186 offset:49168
	ds_read_b128 v[156:159], v187 offset:49168
	ds_read_b128 v[160:163], v186 offset:51216
	ds_read_b128 v[164:167], v187 offset:51216
	ds_read_b128 v[168:171], v186 offset:53264
	ds_read_b128 v[172:175], v187 offset:53264
	ds_read_b128 v[176:179], v186 offset:55312
	ds_read_b128 v[180:183], v187 offset:55312
	s_add_i32 m0, s39, 0x18000
	s_nop 0
	global_load_lds_dwordx4 v184, s[70:71]
	s_add_i32 m0, s39, 0x18400
	s_nop 0
	global_load_lds_dwordx4 v185, s[70:71]
	s_add_u32 s70, s70, 0x80
	s_addc_u32 s71, s71, 0
	s_add_i32 m0, s39, 0x8000
	s_nop 0
	global_load_lds_dwordx4 v184, s[66:67]
	s_add_i32 m0, s39, 0x8400
	s_nop 0
	global_load_lds_dwordx4 v185, s[66:67]
	s_add_u32 s66, s66, 0x80
	s_addc_u32 s67, s67, 0
	s_add_i32 m0, s39, 0x1c000
	s_nop 0
	global_load_lds_dwordx4 v184, s[72:73]
	s_add_i32 m0, s39, 0x1c400
	s_nop 0
	global_load_lds_dwordx4 v185, s[72:73]
	s_add_u32 s72, s72, 0x80
	s_addc_u32 s73, s73, 0
	s_waitcnt lgkmcnt(0)
	s_waitcnt vmcnt(8)
	s_barrier
	s_setprio 1
	v_mfma_f32_16x16x32_bf16 v[88:91], v[0:3], v[152:155], v[88:91]
	v_mfma_f32_16x16x32_bf16 v[92:95], v[8:11], v[152:155], v[92:95]
	v_mfma_f32_16x16x32_bf16 v[96:99], v[0:3], v[160:163], v[96:99]
	v_mfma_f32_16x16x32_bf16 v[100:103], v[8:11], v[160:163], v[100:103]
	v_mfma_f32_16x16x32_bf16 v[104:107], v[0:3], v[168:171], v[104:107]
	v_mfma_f32_16x16x32_bf16 v[108:111], v[8:11], v[168:171], v[108:111]
	v_mfma_f32_16x16x32_bf16 v[112:115], v[0:3], v[176:179], v[112:115]
	v_mfma_f32_16x16x32_bf16 v[116:119], v[8:11], v[176:179], v[116:119]
	v_mfma_f32_16x16x32_bf16 v[88:91], v[4:7], v[156:159], v[88:91]
	v_mfma_f32_16x16x32_bf16 v[92:95], v[12:15], v[156:159], v[92:95]
	v_mfma_f32_16x16x32_bf16 v[96:99], v[4:7], v[164:167], v[96:99]
	v_mfma_f32_16x16x32_bf16 v[100:103], v[12:15], v[164:167], v[100:103]
	v_mfma_f32_16x16x32_bf16 v[104:107], v[4:7], v[172:175], v[104:107]
	v_mfma_f32_16x16x32_bf16 v[108:111], v[12:15], v[172:175], v[108:111]
	v_mfma_f32_16x16x32_bf16 v[112:115], v[4:7], v[180:183], v[112:115]
	v_mfma_f32_16x16x32_bf16 v[116:119], v[12:15], v[180:183], v[116:119]
	v_mfma_f32_16x16x32_bf16 v[120:123], v[196:199], v[152:155], v[120:123]
	v_mfma_f32_16x16x32_bf16 v[124:127], v[204:207], v[152:155], v[124:127]
	v_mfma_f32_16x16x32_bf16 v[128:131], v[196:199], v[160:163], v[128:131]
	v_mfma_f32_16x16x32_bf16 v[132:135], v[204:207], v[160:163], v[132:135]
	v_mfma_f32_16x16x32_bf16 v[136:139], v[196:199], v[168:171], v[136:139]
	v_mfma_f32_16x16x32_bf16 v[140:143], v[204:207], v[168:171], v[140:143]
	v_mfma_f32_16x16x32_bf16 v[144:147], v[196:199], v[176:179], v[144:147]
	v_mfma_f32_16x16x32_bf16 v[148:151], v[204:207], v[176:179], v[148:151]
	v_mfma_f32_16x16x32_bf16 v[120:123], v[200:203], v[156:159], v[120:123]
	v_mfma_f32_16x16x32_bf16 v[124:127], v[208:211], v[156:159], v[124:127]
	v_mfma_f32_16x16x32_bf16 v[128:131], v[200:203], v[164:167], v[128:131]
	v_mfma_f32_16x16x32_bf16 v[132:135], v[208:211], v[164:167], v[132:135]
	v_mfma_f32_16x16x32_bf16 v[136:139], v[200:203], v[172:175], v[136:139]
	v_mfma_f32_16x16x32_bf16 v[140:143], v[208:211], v[172:175], v[140:143]
	v_mfma_f32_16x16x32_bf16 v[144:147], v[200:203], v[180:183], v[144:147]
	v_mfma_f32_16x16x32_bf16 v[148:151], v[208:211], v[180:183], v[148:151]
	s_setprio 0
	s_barrier
	s_sub_u32 s0, s0, 1
	s_branch .Lgu_kloop
